# prompt loop: eight V reads of the next tile prefetched in the tail (all four quads) instead of six
# speedup vs baseline: 1.0005x; 1.0005x over previous
.LBB0_819:
	v_max3_f32 v2, v4, v20, v5
	v_max3_f32 v49, v21, v6, v22
	s_ashr_i32 s21, s4, 1
	v_max3_f32 v2, v2, v7, v23
	v_max3_f32 v49, v49, v8, v24
	s_lshl_b32 s23, s35, 2
	v_max3_f32 v2, v2, v9, v25
	v_max3_f32 v49, v49, v10, v26
	v_and_b32_e32 v88, 16, v48
	v_max3_f32 v2, v2, v11, v27
	v_max3_f32 v49, v49, v12, v28
	s_mov_b32 s4, 1
	v_max3_f32 v2, v2, v13, v29
	v_max3_f32 v49, v49, v14, v30
	s_nop 0
	v_max3_f32 v2, v2, v15, v31
	v_max3_f32 v49, v49, v16, v32
	s_nop 0
	v_max3_f32 v2, v2, v17, v33
	v_max3_f32 v49, v49, v18, v34
	s_nop 0
	v_max3_f32 v2, v2, v49, v19
	s_nop 0
	v_max_f32_e32 v49, v35, v35
	v_max_f32_e32 v2, v2, v2
	v_max_f32_e32 v2, v2, v49
	v_mov_b32_e32 v49, v2
	s_nop 1
	v_permlane32_swap_b32_e32 v2, v49
	v_max_f32_e32 v49, v49, v49
	v_max_f32_e32 v2, v2, v2
	v_max_f32_e32 v2, v2, v49
	v_mul_f32_e32 v2, 0x3f800000, v2
	v_cmp_neq_f32_e32 vcc, s78, v2
	s_cmp_eq_u64 vcc, 0
	v_max_f32_e32 v49, 0xff800000, v2
	s_cselect_b64 vcc, -1, 0
	v_cndmask_b32_e32 v159, v49, v230, vcc
	v_fma_f32 v2, v4, 1.0, -v159
	v_exp_f32_e32 v84, v2
	v_fma_f32 v2, v20, 1.0, -v159
	v_exp_f32_e32 v85, v2
	v_fma_f32 v2, v5, 1.0, -v159
	v_fma_f32 v4, v21, 1.0, -v159
	v_exp_f32_e32 v2, v2
	v_exp_f32_e32 v20, v4
	v_add_f32_e32 v21, v85, v84
	v_cvt_pk_bf16_f32 v144, v84, v2
	v_pk_add_f32 v[4:5], v[20:21], v[2:3]
	v_cvt_pk_bf16_f32 v136, v85, v20
	v_pk_add_f32 v[50:51], v[4:5], v[4:5] op_sel_hi:[0,1]
	v_fma_f32 v4, v6, 1.0, -v159
	v_exp_f32_e32 v21, v4
	v_fma_f32 v4, v22, 1.0, -v159
	v_exp_f32_e32 v86, v4
	v_fma_f32 v4, v7, 1.0, -v159
	v_exp_f32_e32 v50, v4
	v_fma_f32 v4, v23, 1.0, -v159
	v_exp_f32_e32 v6, v4
	v_add_f32_e32 v7, v86, v21
	v_cvt_pk_bf16_f32 v145, v21, v50
	v_pk_add_f32 v[4:5], v[6:7], v[50:51]
	s_nop 0
	v_pk_add_f32 v[22:23], v[4:5], v[4:5] op_sel_hi:[0,1]
	v_fma_f32 v4, v8, 1.0, -v159
	v_exp_f32_e32 v7, v4
	v_fma_f32 v4, v24, 1.0, -v159
	v_exp_f32_e32 v51, v4
	v_fma_f32 v4, v9, 1.0, -v159
	v_exp_f32_e32 v22, v4
	v_fma_f32 v4, v25, 1.0, -v159
	v_exp_f32_e32 v8, v4
	v_add_f32_e32 v9, v51, v7
	v_cvt_pk_bf16_f32 v146, v7, v22
	v_cvt_pk_bf16_f32 v137, v86, v6
	v_pk_add_f32 v[4:5], v[8:9], v[22:23]
	v_cvt_pk_bf16_f32 v138, v51, v8
	v_pk_add_f32 v[24:25], v[4:5], v[4:5] op_sel_hi:[0,1]
	v_fma_f32 v4, v10, 1.0, -v159
	v_exp_f32_e32 v9, v4
	v_fma_f32 v4, v26, 1.0, -v159
	v_exp_f32_e32 v23, v4
	v_fma_f32 v4, v11, 1.0, -v159
	v_exp_f32_e32 v24, v4
	v_fma_f32 v4, v27, 1.0, -v159
	v_exp_f32_e32 v10, v4
	v_lshrrev_b32_e32 v4, 2, v48
	v_add_f32_e32 v11, v23, v9
	v_and_or_b32 v87, v4, 3, v154
	v_pk_add_f32 v[4:5], v[10:11], v[24:25]
	v_lshlrev_b32_e32 v48, 2, v48
	v_pk_add_f32 v[26:27], v[4:5], v[4:5] op_sel_hi:[0,1]
	v_fma_f32 v4, v12, 1.0, -v159
	v_exp_f32_e32 v11, v4
	v_fma_f32 v4, v28, 1.0, -v159
	v_exp_f32_e32 v25, v4
	v_fma_f32 v4, v13, 1.0, -v159
	v_exp_f32_e32 v26, v4
	v_fma_f32 v4, v29, 1.0, -v159
	v_exp_f32_e32 v12, v4
	v_add_f32_e32 v13, v25, v11
	v_mul_u32_u24_e32 v87, 0xc0, v87
	v_cvt_pk_bf16_f32 v147, v9, v24
	v_pk_add_f32 v[4:5], v[12:13], v[26:27]
	v_cvt_pk_bf16_f32 v140, v11, v26
	v_pk_add_f32 v[28:29], v[4:5], v[4:5] op_sel_hi:[0,1]
	v_fma_f32 v4, v14, 1.0, -v159
	v_exp_f32_e32 v13, v4
	v_fma_f32 v4, v30, 1.0, -v159
	v_exp_f32_e32 v27, v4
	v_fma_f32 v4, v15, 1.0, -v159
	v_exp_f32_e32 v28, v4
	v_fma_f32 v4, v31, 1.0, -v159
	v_exp_f32_e32 v14, v4
	v_add_f32_e32 v15, v27, v13
	v_cvt_pk_bf16_f32 v141, v13, v28
	v_cvt_pk_bf16_f32 v139, v23, v10
	v_pk_add_f32 v[4:5], v[14:15], v[28:29]
	v_cvt_pk_bf16_f32 v132, v25, v12
	v_pk_add_f32 v[30:31], v[4:5], v[4:5] op_sel_hi:[0,1]
	v_fma_f32 v4, v16, 1.0, -v159
	v_exp_f32_e32 v15, v4
	v_fma_f32 v4, v32, 1.0, -v159
	v_exp_f32_e32 v29, v4
	v_fma_f32 v4, v17, 1.0, -v159
	v_exp_f32_e32 v30, v4
	v_fma_f32 v4, v33, 1.0, -v159
	v_exp_f32_e32 v16, v4
	v_and_or_b32 v4, v48, 12, v88
	v_add_f32_e32 v17, v29, v15
	v_lshl_or_b32 v162, v4, 1, v87
	v_pk_add_f32 v[4:5], v[16:17], v[30:31]
	v_cvt_pk_bf16_f32 v142, v15, v30
	v_pk_add_f32 v[32:33], v[4:5], v[4:5] op_sel_hi:[0,1]
	v_fma_f32 v4, v18, 1.0, -v159
	v_exp_f32_e32 v17, v4
	v_fma_f32 v4, v34, 1.0, -v159
	v_exp_f32_e32 v31, v4
	v_fma_f32 v4, v19, 1.0, -v159
	v_exp_f32_e32 v32, v4
	v_fma_f32 v4, v35, 1.0, -v159
	v_exp_f32_e32 v18, v4
	v_sub_f32_e32 v4, 0xff800000, v49
	v_exp_f32_e32 v34, v4
	v_add_f32_e32 v19, v31, v17
	v_pk_add_f32 v[4:5], v[18:19], v[32:33]
	v_cvt_pk_bf16_f32 v143, v17, v32
	v_add_f32_e32 v5, v4, v5
	v_mul_f32_e32 v4, 0, v34
	v_cndmask_b32_e64 v4, v4, 0, vcc
	v_add_f32_e32 v152, v4, v5
	v_cvt_pk_bf16_f32 v133, v27, v14
	v_cvt_pk_bf16_f32 v134, v29, v16
	v_cvt_pk_bf16_f32 v135, v31, v18
	v_mad_u64_u32 v[20:21], s[50:51], v45, s80, v[44:45]
	v_mov_b32_e32 v5, v4
	v_mov_b32_e32 v6, v4
	v_mov_b32_e32 v7, v4
	v_mov_b32_e32 v8, v4
	v_mov_b32_e32 v9, v4
	v_mov_b32_e32 v10, v4
	v_mov_b32_e32 v11, v4
	v_mov_b32_e32 v12, v4
	v_mov_b32_e32 v13, v4
	v_mov_b32_e32 v14, v4
	v_mov_b32_e32 v15, v4
	v_mov_b32_e32 v16, v4
	v_mov_b32_e32 v17, v4
	v_mov_b32_e32 v18, v4
	v_mov_b32_e32 v19, v4
	v_add_u32_e32 v151, 0, v20
	s_andn2_b64 vcc, exec, s[2:3]
	s_waitcnt vmcnt(1)
	ds_write_b128 v157, v[40:43]
	ds_write_b64 v158, v[46:47] offset:128
	s_waitcnt vmcnt(0)
	ds_write_b128 v151, v[36:39] offset:26624
	s_waitcnt lgkmcnt(0)
	s_barrier
	s_cbranch_vccnz .LBB0_859
	v_mov_b64_e32 v[34:35], v[18:19]
	v_mov_b64_e32 v[98:99], v[66:67]
	v_mov_b64_e32 v[36:37], v[68:69]
	s_add_i32 s50, s23, -1
	s_mov_b32 s51, 1
	s_mov_b32 s52, s68
	s_mov_b32 s53, s67
	v_mov_b64_e32 v[32:33], v[16:17]
	v_mov_b64_e32 v[30:31], v[14:15]
	v_mov_b64_e32 v[28:29], v[12:13]
	v_mov_b64_e32 v[26:27], v[10:11]
	v_mov_b64_e32 v[24:25], v[8:9]
	v_mov_b64_e32 v[22:23], v[6:7]
	v_mov_b64_e32 v[20:21], v[4:5]
	v_mov_b64_e32 v[96:97], v[64:65]
	v_mov_b64_e32 v[94:95], v[62:63]
	v_mov_b64_e32 v[92:93], v[60:61]
	v_mov_b64_e32 v[90:91], v[58:59]
	v_mov_b64_e32 v[88:89], v[56:57]
	v_mov_b64_e32 v[86:87], v[54:55]
	v_mov_b64_e32 v[84:85], v[52:53]
	v_mov_b64_e32 v[38:39], v[70:71]
	v_mov_b64_e32 v[40:41], v[72:73]
	v_mov_b64_e32 v[42:43], v[74:75]
	v_mov_b64_e32 v[44:45], v[76:77]
	v_mov_b64_e32 v[46:47], v[78:79]
	v_mov_b64_e32 v[48:49], v[80:81]
	v_mov_b64_e32 v[50:51], v[82:83]
	v_xor_b32_e32 v234, 0x80000000, v159
	v_xor_b32_e32 v235, 0x80000000, v159
	v_xor_b32_e32 v236, 0x80000000, v159
	v_xor_b32_e32 v237, 0x80000000, v159
	v_xor_b32_e32 v238, 0x80000000, v159
	v_xor_b32_e32 v239, 0x80000000, v159
	v_xor_b32_e32 v240, 0x80000000, v159
	v_xor_b32_e32 v241, 0x80000000, v159
	v_xor_b32_e32 v242, 0x80000000, v159
	v_xor_b32_e32 v243, 0x80000000, v159
	v_xor_b32_e32 v244, 0x80000000, v159
	v_xor_b32_e32 v245, 0x80000000, v159
	v_xor_b32_e32 v246, 0x80000000, v159
	v_xor_b32_e32 v247, 0x80000000, v159
	v_xor_b32_e32 v248, 0x80000000, v159
	v_xor_b32_e32 v249, 0x80000000, v159
	v_sub_f32_e32 v84, v84, v159
	v_sub_f32_e32 v36, v36, v159
	v_sub_f32_e32 v85, v85, v159
	v_sub_f32_e32 v37, v37, v159
	v_sub_f32_e32 v86, v86, v159
	v_sub_f32_e32 v38, v38, v159
	v_sub_f32_e32 v87, v87, v159
	v_sub_f32_e32 v39, v39, v159
	v_sub_f32_e32 v88, v88, v159
	v_sub_f32_e32 v40, v40, v159
	v_sub_f32_e32 v89, v89, v159
	v_sub_f32_e32 v41, v41, v159
	v_sub_f32_e32 v90, v90, v159
	v_sub_f32_e32 v42, v42, v159
	v_sub_f32_e32 v91, v91, v159
	v_sub_f32_e32 v43, v43, v159
	v_sub_f32_e32 v92, v92, v159
	v_sub_f32_e32 v44, v44, v159
	v_sub_f32_e32 v93, v93, v159
	v_sub_f32_e32 v45, v45, v159
	v_sub_f32_e32 v94, v94, v159
	v_sub_f32_e32 v46, v46, v159
	v_sub_f32_e32 v95, v95, v159
	v_sub_f32_e32 v47, v47, v159
	v_sub_f32_e32 v96, v96, v159
	v_sub_f32_e32 v48, v48, v159
	v_sub_f32_e32 v97, v97, v159
	v_sub_f32_e32 v49, v49, v159
	v_sub_f32_e32 v98, v98, v159
	v_sub_f32_e32 v50, v50, v159
	v_sub_f32_e32 v99, v99, v159
	v_sub_f32_e32 v51, v51, v159
	v_add_u32_e32 v163, 0, v162
	s_add_i32 s2, s52, 0xfffff000
	buffer_load_dwordx2 v[108:109], v161, s[12:15], s2 offen
	s_add_i32 s3, s53, 0xfe020000
	buffer_load_dwordx4 v[104:107], v150, s[12:15], s3 offen
	s_add_i32 s4, s53, 0xfffe0000
	buffer_load_dwordx4 v[100:103], v150, s[12:15], s4 offen
	ds_read_b128 v[200:203], v156 offset:51200
	ds_read_b128 v[204:207], v156 offset:51232
	ds_read_b128 v[208:211], v156 offset:51264
	ds_read_b128 v[212:215], v156 offset:51296
	ds_read_b128 v[216:219], v156 offset:51328
	ds_read_b128 v[250:253], v156 offset:51360
	s_waitcnt lgkmcnt(0)
	ds_read_b64_tr_b16 v[164:165], v162 offset:26624
	ds_read_b64_tr_b16 v[166:167], v162 offset:28160
	ds_read_b64_tr_b16 v[168:169], v162 offset:26688
	ds_read_b64_tr_b16 v[170:171], v162 offset:28224
	ds_read_b64_tr_b16 v[172:173], v162 offset:29696
	ds_read_b64_tr_b16 v[174:175], v162 offset:31232
	ds_read_b64_tr_b16 v[176:177], v162 offset:29760
	ds_read_b64_tr_b16 v[178:179], v162 offset:31296
.LBB0_822:
	s_mov_b32 s5, 0
	v_exp_f32_e32 v124, v84
	v_exp_f32_e32 v125, v85
	v_exp_f32_e32 v126, v86
	v_add_f32_e32 v224, v124, v125
	s_waitcnt lgkmcnt(4)
	v_mfma_f32_32x32x16_bf16 v[4:19], v[164:167], v[144:147], v[4:19]
	ds_read_b64_tr_b16 v[164:165], v162 offset:32768
	ds_read_b64_tr_b16 v[166:167], v162 offset:34304
	v_exp_f32_e32 v127, v87
	v_cvt_pk_bf16_f32 v184, v124, v125
	v_mov_b32_e32 v254, v224
	v_exp_f32_e32 v128, v88
	v_mfma_f32_32x32x16_bf16 v[20:35], v[168:171], v[144:147], v[20:35]
	ds_read_b64_tr_b16 v[168:169], v162 offset:32832
	ds_read_b64_tr_b16 v[170:171], v162 offset:34368
	v_add_f32_e32 v226, v126, v127
	v_exp_f32_e32 v129, v89
	v_cvt_pk_bf16_f32 v185, v126, v127
	v_add_f32_e32 v254, v254, v226
	s_waitcnt lgkmcnt(4)
	v_mfma_f32_32x32x16_bf16 v[4:19], v[172:175], v[140:143], v[4:19]
	ds_read_b64_tr_b16 v[172:173], v162 offset:35840
	ds_read_b64_tr_b16 v[174:175], v162 offset:37376
	v_exp_f32_e32 v130, v90
	v_add_f32_e32 v233, v128, v129
	v_exp_f32_e32 v131, v91
	v_cvt_pk_bf16_f32 v186, v128, v129
	v_mfma_f32_32x32x16_bf16 v[20:35], v[176:179], v[140:143], v[20:35]
	ds_read_b64_tr_b16 v[176:177], v162 offset:35904
	ds_read_b64_tr_b16 v[178:179], v162 offset:37440
	v_add_f32_e32 v254, v254, v233
	v_exp_f32_e32 v124, v92
	v_add_f32_e32 v224, v130, v131
	v_exp_f32_e32 v125, v93
	s_waitcnt lgkmcnt(4)
	v_mfma_f32_32x32x16_bf16 v[4:19], v[164:167], v[136:139], v[4:19]
	ds_read_b128 v[180:183], v155 offset:0
	ds_read_b128 v[112:115], v155 offset:6656
	v_cvt_pk_bf16_f32 v187, v130, v131
	v_add_f32_e32 v254, v254, v224
	v_exp_f32_e32 v126, v94
	v_add_f32_e32 v226, v124, v125
	v_mfma_f32_32x32x16_bf16 v[20:35], v[168:171], v[136:139], v[20:35]
	ds_read_b128 v[116:119], v155 offset:32
	ds_read_b128 v[120:123], v155 offset:6688
	v_exp_f32_e32 v127, v95
	v_cvt_pk_bf16_f32 v188, v124, v125
	v_add_f32_e32 v254, v254, v226
	v_exp_f32_e32 v128, v96
	s_waitcnt lgkmcnt(4)
	v_mfma_f32_32x32x16_bf16 v[4:19], v[172:175], v[132:135], v[4:19]
	v_add_f32_e32 v233, v126, v127
	v_exp_f32_e32 v129, v97
	v_cvt_pk_bf16_f32 v189, v126, v127
	v_add_f32_e32 v254, v254, v233
	v_mfma_f32_32x32x16_bf16 v[20:35], v[176:179], v[132:135], v[20:35]
	v_exp_f32_e32 v130, v98
	v_add_f32_e32 v224, v128, v129
	v_exp_f32_e32 v131, v99
	v_cvt_pk_bf16_f32 v190, v128, v129
	s_waitcnt lgkmcnt(2)
	v_mfma_f32_32x32x16_bf16 v[52:67], v[180:183], v[200:203], v[234:249]
	ds_read_b128 v[180:183], v155 offset:64
	v_add_f32_e32 v254, v254, v224
	v_exp_f32_e32 v124, v36
	v_add_f32_e32 v226, v130, v131
	v_exp_f32_e32 v125, v37
	v_mfma_f32_32x32x16_bf16 v[68:83], v[112:115], v[200:203], v[234:249]
	s_barrier
	s_waitcnt vmcnt(0)
	ds_write_b128 v157, v[104:107] offset:13312
	ds_write_b64 v158, v[108:109] offset:13440
	ds_write_b128 v151, v[100:103] offset:38912
	buffer_load_dwordx2 v[108:109], v161, s[12:15], s52 offen
	s_add_i32 s3, s53, 0xfe040000
	buffer_load_dwordx4 v[104:107], v150, s[12:15], s3 offen
	buffer_load_dwordx4 v[100:103], v150, s[12:15], s53 offen
	ds_read_b128 v[112:115], v155 offset:6720
	v_cvt_pk_bf16_f32 v191, v130, v131
	v_add_f32_e32 v254, v254, v226
	v_exp_f32_e32 v126, v38
	v_add_f32_e32 v233, v124, v125
	s_waitcnt lgkmcnt(5)
	v_mfma_f32_32x32x16_bf16 v[52:67], v[116:119], v[204:207], v[52:67]
	ds_read_b128 v[116:119], v155 offset:96
	v_exp_f32_e32 v127, v39
	v_cvt_pk_bf16_f32 v192, v124, v125
	v_add_f32_e32 v254, v254, v233
	v_exp_f32_e32 v128, v40
	v_mfma_f32_32x32x16_bf16 v[68:83], v[120:123], v[204:207], v[68:83]
	ds_read_b128 v[120:123], v155 offset:6752
	v_add_f32_e32 v224, v126, v127
	v_exp_f32_e32 v129, v41
	v_cvt_pk_bf16_f32 v193, v126, v127
	v_add_f32_e32 v254, v254, v224
	s_waitcnt lgkmcnt(2)
	v_mfma_f32_32x32x16_bf16 v[52:67], v[180:183], v[208:211], v[52:67]
	s_barrier
	ds_read_b128 v[180:183], v155 offset:128
	v_exp_f32_e32 v130, v42
	v_add_f32_e32 v226, v128, v129
	v_exp_f32_e32 v131, v43
	v_cvt_pk_bf16_f32 v194, v128, v129
	v_mfma_f32_32x32x16_bf16 v[68:83], v[112:115], v[208:211], v[68:83]
	ds_read_b128 v[112:115], v155 offset:6784
	v_add_f32_e32 v254, v254, v226
	v_exp_f32_e32 v124, v44
	v_add_f32_e32 v233, v130, v131
	v_exp_f32_e32 v125, v45
	s_waitcnt lgkmcnt(2)
	v_mfma_f32_32x32x16_bf16 v[52:67], v[116:119], v[212:215], v[52:67]
	ds_read_b128 v[116:119], v155 offset:160
	v_cvt_pk_bf16_f32 v195, v130, v131
	v_add_f32_e32 v254, v254, v233
	v_exp_f32_e32 v126, v46
	v_add_f32_e32 v224, v124, v125
	v_mfma_f32_32x32x16_bf16 v[68:83], v[120:123], v[212:215], v[68:83]
	ds_read_b128 v[120:123], v155 offset:6816
	v_exp_f32_e32 v127, v47
	v_cvt_pk_bf16_f32 v196, v124, v125
	v_add_f32_e32 v254, v254, v224
	v_exp_f32_e32 v128, v48
	s_waitcnt lgkmcnt(2)
	v_mfma_f32_32x32x16_bf16 v[52:67], v[180:183], v[216:219], v[52:67]
	v_add_f32_e32 v226, v126, v127
	v_exp_f32_e32 v129, v49
	v_cvt_pk_bf16_f32 v197, v126, v127
	v_add_f32_e32 v254, v254, v226
	v_mfma_f32_32x32x16_bf16 v[68:83], v[112:115], v[216:219], v[68:83]
	v_exp_f32_e32 v130, v50
	v_add_f32_e32 v233, v128, v129
	v_exp_f32_e32 v131, v51
	v_cvt_pk_bf16_f32 v198, v128, v129
	s_waitcnt lgkmcnt(0)
	v_mfma_f32_32x32x16_bf16 v[52:67], v[116:119], v[250:253], v[52:67]
	v_add_f32_e32 v254, v254, v233
	v_add_f32_e32 v224, v130, v131
	v_cvt_pk_bf16_f32 v199, v130, v131
	v_add_f32_e32 v254, v254, v224
	v_mfma_f32_32x32x16_bf16 v[68:83], v[120:123], v[250:253], v[68:83]
	v_cmp_lt_f32_e32 vcc, 0x43800000, v254
	s_cbranch_vccnz .LpfU_s0
.LpfU_b0:
	v_add_f32_e32 v152, v152, v254
	ds_read_b64_tr_b16 v[164:165], v162 offset:38912
	ds_read_b64_tr_b16 v[166:167], v162 offset:40448
	ds_read_b64_tr_b16 v[168:169], v162 offset:38976
	ds_read_b64_tr_b16 v[170:171], v162 offset:40512
	ds_read_b64_tr_b16 v[172:173], v162 offset:41984
	ds_read_b64_tr_b16 v[174:175], v162 offset:43520
	ds_read_b64_tr_b16 v[176:177], v162 offset:42048
	ds_read_b64_tr_b16 v[178:179], v162 offset:43584
	s_cmp_eq_u32 s5, 0
	s_cbranch_scc1 .LpfU_nr0
	s_nop 11
	v_pk_mul_f32 v[4:5], v[220:221], v[4:5] op_sel_hi:[0,1]
	v_pk_mul_f32 v[6:7], v[220:221], v[6:7] op_sel_hi:[0,1]
	v_pk_mul_f32 v[8:9], v[220:221], v[8:9] op_sel_hi:[0,1]
	v_pk_mul_f32 v[10:11], v[220:221], v[10:11] op_sel_hi:[0,1]
	v_pk_mul_f32 v[12:13], v[220:221], v[12:13] op_sel_hi:[0,1]
	v_pk_mul_f32 v[14:15], v[220:221], v[14:15] op_sel_hi:[0,1]
	v_pk_mul_f32 v[16:17], v[220:221], v[16:17] op_sel_hi:[0,1]
	v_pk_mul_f32 v[18:19], v[220:221], v[18:19] op_sel_hi:[0,1]
	v_pk_mul_f32 v[20:21], v[220:221], v[20:21] op_sel_hi:[0,1]
	v_pk_mul_f32 v[22:23], v[220:221], v[22:23] op_sel_hi:[0,1]
	v_pk_mul_f32 v[24:25], v[220:221], v[24:25] op_sel_hi:[0,1]
	v_pk_mul_f32 v[26:27], v[220:221], v[26:27] op_sel_hi:[0,1]
	v_pk_mul_f32 v[28:29], v[220:221], v[28:29] op_sel_hi:[0,1]
	v_pk_mul_f32 v[30:31], v[220:221], v[30:31] op_sel_hi:[0,1]
	v_pk_mul_f32 v[32:33], v[220:221], v[32:33] op_sel_hi:[0,1]
	v_pk_mul_f32 v[34:35], v[220:221], v[34:35] op_sel_hi:[0,1]
	v_sub_f32_e32 v52, v52, v222
	v_sub_f32_e32 v68, v68, v222
	v_sub_f32_e32 v53, v53, v222
	v_sub_f32_e32 v69, v69, v222
	v_sub_f32_e32 v54, v54, v222
	v_sub_f32_e32 v70, v70, v222
	v_sub_f32_e32 v55, v55, v222
	v_sub_f32_e32 v71, v71, v222
	v_sub_f32_e32 v56, v56, v222
	v_sub_f32_e32 v72, v72, v222
	v_sub_f32_e32 v57, v57, v222
	v_sub_f32_e32 v73, v73, v222
	v_sub_f32_e32 v58, v58, v222
	v_sub_f32_e32 v74, v74, v222
	v_sub_f32_e32 v59, v59, v222
	v_sub_f32_e32 v75, v75, v222
	v_sub_f32_e32 v60, v60, v222
	v_sub_f32_e32 v76, v76, v222
	v_sub_f32_e32 v61, v61, v222
	v_sub_f32_e32 v77, v77, v222
	v_sub_f32_e32 v62, v62, v222
	v_sub_f32_e32 v78, v78, v222
	v_sub_f32_e32 v63, v63, v222
	v_sub_f32_e32 v79, v79, v222
	v_sub_f32_e32 v64, v64, v222
	v_sub_f32_e32 v80, v80, v222
	v_sub_f32_e32 v65, v65, v222
	v_sub_f32_e32 v81, v81, v222
	v_sub_f32_e32 v66, v66, v222
	v_sub_f32_e32 v82, v82, v222
	v_sub_f32_e32 v67, v67, v222
	v_sub_f32_e32 v83, v83, v222
	v_sub_f32_e32 v234, v234, v222
	v_sub_f32_e32 v235, v235, v222
	v_sub_f32_e32 v236, v236, v222
	v_sub_f32_e32 v237, v237, v222
	v_sub_f32_e32 v238, v238, v222
	v_sub_f32_e32 v239, v239, v222
	v_sub_f32_e32 v240, v240, v222
	v_sub_f32_e32 v241, v241, v222
	v_sub_f32_e32 v242, v242, v222
	v_sub_f32_e32 v243, v243, v222
	v_sub_f32_e32 v244, v244, v222
	v_sub_f32_e32 v245, v245, v222
	v_sub_f32_e32 v246, v246, v222
	v_sub_f32_e32 v247, v247, v222
	v_sub_f32_e32 v248, v248, v222
	v_sub_f32_e32 v249, v249, v222
.LpfU_nr0:
	s_mov_b32 s5, 0
	v_exp_f32_e32 v124, v52
	v_exp_f32_e32 v125, v53
	v_exp_f32_e32 v126, v54
	v_add_f32_e32 v224, v124, v125
	s_waitcnt lgkmcnt(4)
	v_mfma_f32_32x32x16_bf16 v[4:19], v[164:167], v[184:187], v[4:19]
	ds_read_b64_tr_b16 v[164:165], v162 offset:45056
	ds_read_b64_tr_b16 v[166:167], v162 offset:46592
	v_exp_f32_e32 v127, v55
	v_cvt_pk_bf16_f32 v144, v124, v125
	v_mov_b32_e32 v254, v224
	v_exp_f32_e32 v128, v56
	v_mfma_f32_32x32x16_bf16 v[20:35], v[168:171], v[184:187], v[20:35]
	ds_read_b64_tr_b16 v[168:169], v162 offset:45120
	ds_read_b64_tr_b16 v[170:171], v162 offset:46656
	v_add_f32_e32 v226, v126, v127
	v_exp_f32_e32 v129, v57
	v_cvt_pk_bf16_f32 v145, v126, v127
	v_add_f32_e32 v254, v254, v226
	s_waitcnt lgkmcnt(4)
	v_mfma_f32_32x32x16_bf16 v[4:19], v[172:175], v[188:191], v[4:19]
	ds_read_b64_tr_b16 v[172:173], v162 offset:48128
	ds_read_b64_tr_b16 v[174:175], v162 offset:49664
	v_exp_f32_e32 v130, v58
	v_add_f32_e32 v233, v128, v129
	v_exp_f32_e32 v131, v59
	v_cvt_pk_bf16_f32 v146, v128, v129
	v_mfma_f32_32x32x16_bf16 v[20:35], v[176:179], v[188:191], v[20:35]
	ds_read_b64_tr_b16 v[176:177], v162 offset:48192
	ds_read_b64_tr_b16 v[178:179], v162 offset:49728
	v_add_f32_e32 v254, v254, v233
	v_exp_f32_e32 v124, v60
	v_add_f32_e32 v224, v130, v131
	v_exp_f32_e32 v125, v61
	s_waitcnt lgkmcnt(4)
	v_mfma_f32_32x32x16_bf16 v[4:19], v[164:167], v[192:195], v[4:19]
	ds_read_b128 v[180:183], v155 offset:13312
	ds_read_b128 v[112:115], v155 offset:19968
	v_cvt_pk_bf16_f32 v147, v130, v131
	v_add_f32_e32 v254, v254, v224
	v_exp_f32_e32 v126, v62
	v_add_f32_e32 v226, v124, v125
	v_mfma_f32_32x32x16_bf16 v[20:35], v[168:171], v[192:195], v[20:35]
	ds_read_b128 v[116:119], v155 offset:13344
	ds_read_b128 v[120:123], v155 offset:20000
	v_exp_f32_e32 v127, v63
	v_cvt_pk_bf16_f32 v140, v124, v125
	v_add_f32_e32 v254, v254, v226
	v_exp_f32_e32 v128, v64
	s_waitcnt lgkmcnt(4)
	v_mfma_f32_32x32x16_bf16 v[4:19], v[172:175], v[196:199], v[4:19]
	v_add_f32_e32 v233, v126, v127
	v_exp_f32_e32 v129, v65
	v_cvt_pk_bf16_f32 v141, v126, v127
	v_add_f32_e32 v254, v254, v233
	v_mfma_f32_32x32x16_bf16 v[20:35], v[176:179], v[196:199], v[20:35]
	v_exp_f32_e32 v130, v66
	v_add_f32_e32 v224, v128, v129
	v_exp_f32_e32 v131, v67
	v_cvt_pk_bf16_f32 v142, v128, v129
	s_waitcnt lgkmcnt(2)
	v_mfma_f32_32x32x16_bf16 v[84:99], v[180:183], v[200:203], v[234:249]
	ds_read_b128 v[180:183], v155 offset:13376
	v_add_f32_e32 v254, v254, v224
	v_exp_f32_e32 v124, v68
	v_add_f32_e32 v226, v130, v131
	v_exp_f32_e32 v125, v69
	v_mfma_f32_32x32x16_bf16 v[36:51], v[112:115], v[200:203], v[234:249]
	s_barrier
	s_waitcnt vmcnt(0)
	ds_write_b128 v157, v[104:107]
	ds_write_b64 v158, v[108:109] offset:128
	ds_write_b128 v151, v[100:103] offset:26624
	s_add_i32 s2, s51, 2
	s_cmp_lt_i32 s2, s50
	s_cbranch_scc0 .LpfU_nl
	s_add_i32 s2, s52, 0x1000
	buffer_load_dwordx2 v[108:109], v161, s[12:15], s2 offen
	s_add_i32 s3, s53, 0xfe060000
	buffer_load_dwordx4 v[104:107], v150, s[12:15], s3 offen
	s_add_i32 s4, s53, 0x20000
	buffer_load_dwordx4 v[100:103], v150, s[12:15], s4 offen

.LpfU_b1:
	v_add_f32_e32 v152, v152, v254
	ds_read_b64_tr_b16 v[164:165], v162 offset:26624
	ds_read_b64_tr_b16 v[166:167], v162 offset:28160
	ds_read_b64_tr_b16 v[168:169], v162 offset:26688
	ds_read_b64_tr_b16 v[170:171], v162 offset:28224
	ds_read_b64_tr_b16 v[172:173], v162 offset:29696
	ds_read_b64_tr_b16 v[174:175], v162 offset:31232
	ds_read_b64_tr_b16 v[176:177], v162 offset:29760
	ds_read_b64_tr_b16 v[178:179], v162 offset:31296
	s_cmp_eq_u32 s5, 0
	s_cbranch_scc1 .LpfU_nr1
	s_nop 11
	v_pk_mul_f32 v[4:5], v[220:221], v[4:5] op_sel_hi:[0,1]
	v_pk_mul_f32 v[6:7], v[220:221], v[6:7] op_sel_hi:[0,1]
	v_pk_mul_f32 v[8:9], v[220:221], v[8:9] op_sel_hi:[0,1]
	v_pk_mul_f32 v[10:11], v[220:221], v[10:11] op_sel_hi:[0,1]
	v_pk_mul_f32 v[12:13], v[220:221], v[12:13] op_sel_hi:[0,1]
	v_pk_mul_f32 v[14:15], v[220:221], v[14:15] op_sel_hi:[0,1]
	v_pk_mul_f32 v[16:17], v[220:221], v[16:17] op_sel_hi:[0,1]
	v_pk_mul_f32 v[18:19], v[220:221], v[18:19] op_sel_hi:[0,1]
	v_pk_mul_f32 v[20:21], v[220:221], v[20:21] op_sel_hi:[0,1]
	v_pk_mul_f32 v[22:23], v[220:221], v[22:23] op_sel_hi:[0,1]
	v_pk_mul_f32 v[24:25], v[220:221], v[24:25] op_sel_hi:[0,1]
	v_pk_mul_f32 v[26:27], v[220:221], v[26:27] op_sel_hi:[0,1]
	v_pk_mul_f32 v[28:29], v[220:221], v[28:29] op_sel_hi:[0,1]
	v_pk_mul_f32 v[30:31], v[220:221], v[30:31] op_sel_hi:[0,1]
	v_pk_mul_f32 v[32:33], v[220:221], v[32:33] op_sel_hi:[0,1]
	v_pk_mul_f32 v[34:35], v[220:221], v[34:35] op_sel_hi:[0,1]
	v_sub_f32_e32 v84, v84, v222
	v_sub_f32_e32 v36, v36, v222
	v_sub_f32_e32 v85, v85, v222
	v_sub_f32_e32 v37, v37, v222
	v_sub_f32_e32 v86, v86, v222
	v_sub_f32_e32 v38, v38, v222
	v_sub_f32_e32 v87, v87, v222
	v_sub_f32_e32 v39, v39, v222
	v_sub_f32_e32 v88, v88, v222
	v_sub_f32_e32 v40, v40, v222
	v_sub_f32_e32 v89, v89, v222
	v_sub_f32_e32 v41, v41, v222
	v_sub_f32_e32 v90, v90, v222
	v_sub_f32_e32 v42, v42, v222
	v_sub_f32_e32 v91, v91, v222
	v_sub_f32_e32 v43, v43, v222
	v_sub_f32_e32 v92, v92, v222
	v_sub_f32_e32 v44, v44, v222
	v_sub_f32_e32 v93, v93, v222
	v_sub_f32_e32 v45, v45, v222
	v_sub_f32_e32 v94, v94, v222
	v_sub_f32_e32 v46, v46, v222
	v_sub_f32_e32 v95, v95, v222
	v_sub_f32_e32 v47, v47, v222
	v_sub_f32_e32 v96, v96, v222
	v_sub_f32_e32 v48, v48, v222
	v_sub_f32_e32 v97, v97, v222
	v_sub_f32_e32 v49, v49, v222
	v_sub_f32_e32 v98, v98, v222
	v_sub_f32_e32 v50, v50, v222
	v_sub_f32_e32 v99, v99, v222
	v_sub_f32_e32 v51, v51, v222
	v_sub_f32_e32 v234, v234, v222
	v_sub_f32_e32 v235, v235, v222
	v_sub_f32_e32 v236, v236, v222
	v_sub_f32_e32 v237, v237, v222
	v_sub_f32_e32 v238, v238, v222
	v_sub_f32_e32 v239, v239, v222
	v_sub_f32_e32 v240, v240, v222
	v_sub_f32_e32 v241, v241, v222
	v_sub_f32_e32 v242, v242, v222
	v_sub_f32_e32 v243, v243, v222
	v_sub_f32_e32 v244, v244, v222
	v_sub_f32_e32 v245, v245, v222
	v_sub_f32_e32 v246, v246, v222
	v_sub_f32_e32 v247, v247, v222
	v_sub_f32_e32 v248, v248, v222
	v_sub_f32_e32 v249, v249, v222
